# heavy diff loop: each 8-read V-fragment LDS burst moved behind the first MFMA of its group (MFMA issues earlier), on top of x loads nt
# speedup vs baseline: 1.0059x; 1.0059x over previous
.LBB0_301:
	s_add_i32 s81, s70, s74
	s_add_i32 s82, s81, -2
	s_add_i32 s4, s81, -4
	s_cmp_lt_i32 s4, s68
	s_cselect_b32 s4, s4, s82
	s_add_i32 s5, s81, -3
	s_add_i32 s8, s81, -1
	s_cmp_lt_i32 s5, s68
	s_cselect_b32 s80, s5, s8
	v_lshl_add_u32 v96, s80, 13, v185
	s_mov_b32 s5, m0
	s_mov_b32 m0, s76
	s_nop 0
	global_load_lds_dwordx4 v96, s[22:23]
	s_mov_b32 m0, s5
	v_exp_f32_e32 v80, v80
	s_mov_b32 s5, m0
	s_mov_b32 m0, s77
	s_nop 0
	global_load_lds_dwordx4 v96, s[24:25]
	s_mov_b32 m0, s5
	s_lshl_b32 s5, s4, 14
	v_add_u32_e32 v96, s5, v170
	s_mov_b32 s8, m0
	s_mov_b32 m0, s71
	s_nop 0
	global_load_lds_dwordx4 v96, s[6:7]
	s_mov_b32 m0, s8
	v_add_u32_e32 v96, s5, v169
	s_mov_b32 s5, m0
	s_mov_b32 m0, s72
	s_nop 0
	global_load_lds_dwordx4 v96, s[6:7]
	s_mov_b32 m0, s5
	s_lshl_b32 s5, s4, 6
	s_cmp_lt_i32 s4, s68
	v_subrev_u32_e32 v96, s5, v159
	v_sub_u32_e32 v97, 0, v96
	s_cselect_b64 s[4:5], -1, 0
	v_cndmask_b32_e64 v96, v97, v96, s[4:5]
	v_cvt_f32_i32_e32 v96, v96
	v_cndmask_b32_e64 v99, v187, v186, s[4:5]
	v_cndmask_b32_e32 v128, 0, v99, vcc
	ds_read_b128 v[200:203], v171
	ds_read_b128 v[204:207], v171 offset:4096
	ds_read_b128 v[208:211], v174
	ds_read_b128 v[212:215], v174 offset:4096
	v_mul_f32_e64 v97, -v160, v96
	v_cvt_pk_bf16_f32 v97, v97, 0
	v_lshlrev_b32_e32 v97, 16, v97
	v_fma_f32 v96, -v160, v96, -v97
	v_cvt_pk_bf16_f32 v98, v96, 0
	v_lshlrev_b32_e32 v98, 16, v98
	v_sub_f32_e32 v96, v96, v98
	v_cvt_pk_bf16_f32 v97, v97, v98
	v_cvt_pk_bf16_f32 v96, v96, 0
	v_cndmask_b32_e32 v129, 0, v97, vcc
	v_cndmask_b32_e32 v130, 0, v96, vcc
	v_exp_f32_e32 v81, v81
	s_nop 0
	v_mfma_f32_32x32x16_bf16 v[112:127], v[152:155], v[128:131], 0
	v_mfma_f32_32x32x16_bf16 v[96:111], v[148:151], v[128:131], 0
	v_exp_f32_e32 v82, v82
	v_exp_f32_e32 v83, v83
	s_waitcnt lgkmcnt(3)
	v_mfma_f32_32x32x16_bf16 v[112:127], v[200:203], v[144:147], v[112:127]
	ds_read_b128 v[216:219], v172
	ds_read_b128 v[220:223], v172 offset:4096
	ds_read_b128 v[224:227], v173
	ds_read_b128 v[228:231], v173 offset:4096
	v_exp_f32_e32 v84, v84
	v_exp_f32_e32 v85, v85
	s_waitcnt lgkmcnt(6)
	v_mfma_f32_32x32x16_bf16 v[96:111], v[204:207], v[144:147], v[96:111]
	v_exp_f32_e32 v86, v86
	v_exp_f32_e32 v87, v87
	v_cvt_pk_bf16_f32 v200, v80, v81
	v_cvt_pk_bf16_f32 v201, v82, v83
	v_cvt_pk_bf16_f32 v202, v84, v85
	v_cvt_pk_bf16_f32 v203, v86, v87
	s_waitcnt lgkmcnt(5)
	v_mfma_f32_32x32x16_bf16 v[112:127], v[208:211], v[140:143], v[112:127]
	v_exp_f32_e32 v88, v88
	v_exp_f32_e32 v89, v89
	s_waitcnt lgkmcnt(4)
	v_mfma_f32_32x32x16_bf16 v[96:111], v[212:215], v[140:143], v[96:111]
	v_exp_f32_e32 v90, v90
	v_exp_f32_e32 v91, v91
	s_waitcnt lgkmcnt(3)
	v_mfma_f32_32x32x16_bf16 v[112:127], v[216:219], v[136:139], v[112:127]
	ds_read_b64_tr_b16 v[204:205], v175 offset:49152
	ds_read_b64_tr_b16 v[206:207], v176 offset:49152
	ds_read_b64_tr_b16 v[208:209], v177 offset:49152
	ds_read_b64_tr_b16 v[210:211], v178 offset:49152
	ds_read_b64_tr_b16 v[212:213], v179 offset:49152
	ds_read_b64_tr_b16 v[214:215], v182 offset:49152
	ds_read_b64_tr_b16 v[232:233], v183 offset:49152
	ds_read_b64_tr_b16 v[234:235], v184 offset:49152
	v_exp_f32_e32 v92, v92
	v_exp_f32_e32 v93, v93
	s_waitcnt lgkmcnt(10)
	v_mfma_f32_32x32x16_bf16 v[96:111], v[220:223], v[136:139], v[96:111]
	v_exp_f32_e32 v94, v94
	v_exp_f32_e32 v95, v95
	v_cvt_pk_bf16_f32 v216, v88, v89
	v_cvt_pk_bf16_f32 v217, v90, v91
	v_cvt_pk_bf16_f32 v218, v92, v93
	v_cvt_pk_bf16_f32 v219, v94, v95
	s_waitcnt lgkmcnt(9)
	v_mfma_f32_32x32x16_bf16 v[112:127], v[224:227], v[132:135], v[112:127]
	s_waitcnt lgkmcnt(8)
	v_mfma_f32_32x32x16_bf16 v[96:111], v[228:231], v[132:135], v[96:111]
	s_waitcnt lgkmcnt(6)
	v_mfma_f32_32x32x16_bf16 v[48:63], v[204:207], v[200:203], v[48:63]
	ds_read_b64_tr_b16 v[220:221], v175 offset:53248
	ds_read_b64_tr_b16 v[222:223], v176 offset:53248
	ds_read_b64_tr_b16 v[224:225], v177 offset:53248
	ds_read_b64_tr_b16 v[226:227], v178 offset:53248
	ds_read_b64_tr_b16 v[228:229], v179 offset:53248
	ds_read_b64_tr_b16 v[230:231], v182 offset:53248
	ds_read_b64_tr_b16 v[236:237], v183 offset:53248
	ds_read_b64_tr_b16 v[238:239], v184 offset:53248
	v_exp_f32_e32 v64, v64
	v_exp_f32_e32 v65, v65
	s_waitcnt lgkmcnt(12)
	v_mfma_f32_32x32x16_bf16 v[32:47], v[208:211], v[200:203], v[32:47]
	v_exp_f32_e32 v66, v66
	v_exp_f32_e32 v67, v67
	s_waitcnt lgkmcnt(10)
	v_mfma_f32_32x32x16_bf16 v[16:31], v[212:215], v[200:203], v[16:31]
	v_exp_f32_e32 v68, v68
	v_exp_f32_e32 v69, v69
	s_waitcnt lgkmcnt(8)
	v_mfma_f32_32x32x16_bf16 v[0:15], v[232:235], v[200:203], v[0:15]
	v_exp_f32_e32 v70, v70
	v_exp_f32_e32 v71, v71
	v_cvt_pk_bf16_f32 v204, v64, v65
	v_cvt_pk_bf16_f32 v205, v66, v67
	v_cvt_pk_bf16_f32 v206, v68, v69
	v_cvt_pk_bf16_f32 v207, v70, v71
	s_waitcnt lgkmcnt(6)
	v_mfma_f32_32x32x16_bf16 v[48:63], v[220:223], v[216:219], v[48:63]
	ds_read_b64_tr_b16 v[200:201], v175 offset:57344
	ds_read_b64_tr_b16 v[202:203], v176 offset:57344
	ds_read_b64_tr_b16 v[208:209], v177 offset:57344
	ds_read_b64_tr_b16 v[210:211], v178 offset:57344
	ds_read_b64_tr_b16 v[212:213], v179 offset:57344
	ds_read_b64_tr_b16 v[214:215], v182 offset:57344
	ds_read_b64_tr_b16 v[232:233], v183 offset:57344
	ds_read_b64_tr_b16 v[234:235], v184 offset:57344
	v_exp_f32_e32 v72, v72
	s_waitcnt lgkmcnt(12)
	v_mfma_f32_32x32x16_bf16 v[32:47], v[224:227], v[216:219], v[32:47]
	v_exp_f32_e32 v73, v73
	s_waitcnt lgkmcnt(10)
	v_mfma_f32_32x32x16_bf16 v[16:31], v[228:231], v[216:219], v[16:31]
	v_exp_f32_e32 v74, v74
	s_waitcnt lgkmcnt(8)
	v_mfma_f32_32x32x16_bf16 v[0:15], v[236:239], v[216:219], v[0:15]
	v_exp_f32_e32 v75, v75
	s_waitcnt lgkmcnt(6)
	v_mfma_f32_32x32x16_bf16 v[48:63], v[200:203], v[204:207], v[48:63]
	ds_read_b64_tr_b16 v[216:217], v175 offset:61440
	ds_read_b64_tr_b16 v[218:219], v176 offset:61440
	ds_read_b64_tr_b16 v[220:221], v177 offset:61440
	ds_read_b64_tr_b16 v[222:223], v178 offset:61440
	ds_read_b64_tr_b16 v[224:225], v179 offset:61440
	ds_read_b64_tr_b16 v[226:227], v182 offset:61440
	ds_read_b64_tr_b16 v[228:229], v183 offset:61440
	ds_read_b64_tr_b16 v[230:231], v184 offset:61440
	v_exp_f32_e32 v76, v76
	s_waitcnt lgkmcnt(12)
	v_mfma_f32_32x32x16_bf16 v[32:47], v[208:211], v[204:207], v[32:47]
	v_exp_f32_e32 v77, v77
	s_waitcnt lgkmcnt(10)
	v_mfma_f32_32x32x16_bf16 v[16:31], v[212:215], v[204:207], v[16:31]
	v_exp_f32_e32 v78, v78
	s_waitcnt lgkmcnt(8)
	v_mfma_f32_32x32x16_bf16 v[0:15], v[232:235], v[204:207], v[0:15]
	v_exp_f32_e32 v79, v79
	v_cvt_pk_bf16_f32 v200, v72, v73
	v_cvt_pk_bf16_f32 v201, v74, v75
	v_cvt_pk_bf16_f32 v202, v76, v77
	v_cvt_pk_bf16_f32 v203, v78, v79
	s_waitcnt lgkmcnt(6)
	s_nop 0
	v_mfma_f32_32x32x16_bf16 v[48:63], v[216:219], v[200:203], v[48:63]
	s_waitcnt lgkmcnt(4)
	v_mfma_f32_32x32x16_bf16 v[32:47], v[220:223], v[200:203], v[32:47]
	s_waitcnt lgkmcnt(2)
	v_mfma_f32_32x32x16_bf16 v[16:31], v[224:227], v[200:203], v[16:31]
	s_waitcnt lgkmcnt(0)
	v_mfma_f32_32x32x16_bf16 v[0:15], v[228:231], v[200:203], v[0:15]
	s_waitcnt vmcnt(0) lgkmcnt(0)
	s_barrier
	s_cmp_ge_i32 s74, s20
	s_cbranch_scc1 .LBB0_303
	s_cmp_lt_i32 s82, s68
	s_cselect_b32 s4, s82, s81
	v_lshl_add_u32 v128, s4, 13, v185
	s_mov_b32 s4, m0
	s_mov_b32 m0, s73
	s_nop 0
	global_load_lds_dwordx4 v128, s[22:23]
	s_mov_b32 m0, s4
	s_nop 0
	s_mov_b32 s4, m0
	s_mov_b32 m0, s75
	s_nop 0
	global_load_lds_dwordx4 v128, s[24:25]
	s_mov_b32 m0, s4
.LBB0_303:
	v_add_f32_e32 v80, 0, v80
	v_add_f32_e32 v80, v81, v80
	v_add_f32_e32 v80, v82, v80
	v_add_f32_e32 v80, v83, v80
	v_add_f32_e32 v80, v84, v80
	v_add_f32_e32 v80, v85, v80
	v_add_f32_e32 v80, v86, v80
	v_add_f32_e32 v80, v87, v80
	v_add_f32_e32 v80, v88, v80
	v_add_f32_e32 v80, v89, v80
	v_add_f32_e32 v80, v90, v80
	v_add_f32_e32 v80, v91, v80
	v_add_f32_e32 v80, v92, v80
	v_add_f32_e32 v80, v93, v80
	v_add_f32_e32 v80, v94, v80
	v_add_f32_e32 v80, v95, v80
	v_add_f32_e32 v64, v64, v80
	v_add_f32_e32 v64, v65, v64
	v_add_f32_e32 v64, v66, v64
	v_add_f32_e32 v64, v67, v64
	v_add_f32_e32 v64, v68, v64
	v_add_f32_e32 v64, v69, v64
	v_add_f32_e32 v64, v70, v64
	v_add_f32_e32 v64, v71, v64
	v_add_f32_e32 v64, v72, v64
	v_add_f32_e32 v64, v73, v64
	v_add_f32_e32 v64, v74, v64
	v_add_f32_e32 v64, v75, v64
	v_add_f32_e32 v64, v76, v64
	v_add_f32_e32 v64, v77, v64
	v_add_f32_e32 v64, v78, v64
	v_add_f32_e32 v64, v79, v64
	s_lshl_b32 s4, s80, 14
	v_add_f32_e32 v192, v188, v64
	v_add_u32_e32 v64, s4, v170
	s_mov_b32 s5, m0
	s_mov_b32 m0, s78
	s_nop 0
	global_load_lds_dwordx4 v64, s[6:7]
	s_mov_b32 m0, s5
	v_add_u32_e32 v64, s4, v169
	s_mov_b32 s4, m0
	s_mov_b32 m0, s79
	s_nop 0
	global_load_lds_dwordx4 v64, s[6:7]
	s_mov_b32 m0, s4
	s_lshl_b32 s4, s80, 6
	s_cmp_lt_i32 s80, s68
	v_subrev_u32_e32 v64, s4, v159
	v_sub_u32_e32 v65, 0, v64
	s_cselect_b64 s[4:5], -1, 0
	v_cndmask_b32_e64 v64, v65, v64, s[4:5]
	v_cvt_f32_i32_e32 v64, v64
	v_cndmask_b32_e64 v67, v187, v186, s[4:5]
	v_cndmask_b32_e32 v128, 0, v67, vcc
	ds_read_b128 v[188:191], v171 offset:32768
	ds_read_b128 v[200:203], v171 offset:36864
	ds_read_b128 v[204:207], v174 offset:32768
	ds_read_b128 v[208:211], v174 offset:36864
	v_mul_f32_e64 v65, -v160, v64
	v_cvt_pk_bf16_f32 v65, v65, 0
	v_lshlrev_b32_e32 v65, 16, v65
	v_fma_f32 v64, -v160, v64, -v65
	v_cvt_pk_bf16_f32 v66, v64, 0
	v_lshlrev_b32_e32 v66, 16, v66
	v_sub_f32_e32 v64, v64, v66
	v_cvt_pk_bf16_f32 v65, v65, v66
	v_cvt_pk_bf16_f32 v64, v64, 0
	v_cndmask_b32_e32 v129, 0, v65, vcc
	v_cndmask_b32_e32 v130, 0, v64, vcc
	v_exp_f32_e32 v224, v112
	v_exp_f32_e32 v225, v113
	v_mfma_f32_32x32x16_bf16 v[80:95], v[152:155], v[128:131], 0
	v_add_f32_e32 v64, 0, v224
	v_add_f32_e32 v64, v225, v64
	v_exp_f32_e32 v226, v114
	v_exp_f32_e32 v227, v115
	v_add_f32_e32 v64, v226, v64
	v_add_f32_e32 v228, v227, v64
	v_mfma_f32_32x32x16_bf16 v[64:79], v[148:151], v[128:131], 0
	s_waitcnt lgkmcnt(3)
	v_mfma_f32_32x32x16_bf16 v[80:95], v[188:191], v[144:147], v[80:95]
	ds_read_b128 v[112:115], v172 offset:32768
	ds_read_b128 v[212:215], v172 offset:36864
	ds_read_b128 v[216:219], v173 offset:32768
	ds_read_b128 v[220:223], v173 offset:36864
	v_exp_f32_e32 v128, v116
	v_exp_f32_e32 v129, v117
	v_add_f32_e32 v116, v128, v228
	v_add_f32_e32 v130, v129, v116
	s_waitcnt lgkmcnt(6)
	v_mfma_f32_32x32x16_bf16 v[64:79], v[200:203], v[144:147], v[64:79]
	v_exp_f32_e32 v188, v118
	v_exp_f32_e32 v119, v119
	v_cvt_pk_bf16_f32 v116, v224, v225
	v_cvt_pk_bf16_f32 v117, v226, v227
	v_add_f32_e32 v118, v188, v130
	v_add_f32_e32 v130, v119, v118
	v_cvt_pk_bf16_f32 v118, v128, v129
	v_cvt_pk_bf16_f32 v119, v188, v119
	s_waitcnt lgkmcnt(5)
	v_mfma_f32_32x32x16_bf16 v[80:95], v[204:207], v[140:143], v[80:95]
	v_exp_f32_e32 v128, v120
	v_exp_f32_e32 v129, v121
	v_add_f32_e32 v120, v128, v130
	v_add_f32_e32 v120, v129, v120
	s_waitcnt lgkmcnt(4)
	v_mfma_f32_32x32x16_bf16 v[64:79], v[208:211], v[140:143], v[64:79]
	v_exp_f32_e32 v130, v122
	v_exp_f32_e32 v224, v123
	v_add_f32_e32 v120, v130, v120
	v_add_f32_e32 v225, v224, v120
	s_waitcnt lgkmcnt(3)
	v_mfma_f32_32x32x16_bf16 v[80:95], v[112:115], v[136:139], v[80:95]
	ds_read_b64_tr_b16 v[120:121], v175 offset:16384
	ds_read_b64_tr_b16 v[122:123], v176 offset:16384
	ds_read_b64_tr_b16 v[188:189], v177 offset:16384
	ds_read_b64_tr_b16 v[190:191], v178 offset:16384
	ds_read_b64_tr_b16 v[200:201], v179 offset:16384
	ds_read_b64_tr_b16 v[202:203], v182 offset:16384
	ds_read_b64_tr_b16 v[204:205], v183 offset:16384
	ds_read_b64_tr_b16 v[206:207], v184 offset:16384
	v_exp_f32_e32 v124, v124
	v_exp_f32_e32 v125, v125
	v_add_f32_e32 v112, v124, v225
	v_add_f32_e32 v114, v125, v112
	s_waitcnt lgkmcnt(10)
	v_mfma_f32_32x32x16_bf16 v[64:79], v[212:215], v[136:139], v[64:79]
	v_exp_f32_e32 v115, v126
	v_exp_f32_e32 v126, v127
	v_cvt_pk_bf16_f32 v112, v128, v129
	v_cvt_pk_bf16_f32 v113, v130, v224
	v_add_f32_e32 v114, v115, v114
	v_add_f32_e32 v128, v126, v114
	v_cvt_pk_bf16_f32 v114, v124, v125
	v_cvt_pk_bf16_f32 v115, v115, v126
	s_waitcnt lgkmcnt(9)
	v_mfma_f32_32x32x16_bf16 v[80:95], v[216:219], v[132:135], v[80:95]
	s_waitcnt lgkmcnt(8)
	v_mfma_f32_32x32x16_bf16 v[64:79], v[220:223], v[132:135], v[64:79]
	s_waitcnt lgkmcnt(6)
	v_mfma_f32_32x32x16_bf16 v[48:63], v[120:123], v[116:119], v[48:63]
	ds_read_b64_tr_b16 v[124:125], v175 offset:20480
	ds_read_b64_tr_b16 v[126:127], v176 offset:20480
	ds_read_b64_tr_b16 v[208:209], v177 offset:20480
	ds_read_b64_tr_b16 v[210:211], v178 offset:20480
	ds_read_b64_tr_b16 v[212:213], v179 offset:20480
	ds_read_b64_tr_b16 v[214:215], v182 offset:20480
	ds_read_b64_tr_b16 v[216:217], v183 offset:20480
	ds_read_b64_tr_b16 v[218:219], v184 offset:20480
	v_exp_f32_e32 v96, v96
	v_exp_f32_e32 v97, v97
	v_add_f32_e32 v120, v96, v128
	v_add_f32_e32 v120, v97, v120
	s_waitcnt lgkmcnt(12)
	v_mfma_f32_32x32x16_bf16 v[32:47], v[188:191], v[116:119], v[32:47]
	v_exp_f32_e32 v98, v98
	v_exp_f32_e32 v99, v99
	v_add_f32_e32 v120, v98, v120
	v_add_f32_e32 v120, v99, v120
	s_waitcnt lgkmcnt(10)
	v_mfma_f32_32x32x16_bf16 v[16:31], v[200:203], v[116:119], v[16:31]
	v_exp_f32_e32 v100, v100
	v_exp_f32_e32 v101, v101
	v_add_f32_e32 v120, v100, v120
	v_add_f32_e32 v120, v101, v120
	s_waitcnt lgkmcnt(8)
	v_mfma_f32_32x32x16_bf16 v[0:15], v[204:207], v[116:119], v[0:15]
	v_exp_f32_e32 v102, v102
	v_exp_f32_e32 v103, v103
	v_cvt_pk_bf16_f32 v96, v96, v97
	v_cvt_pk_bf16_f32 v97, v98, v99
	v_add_f32_e32 v98, v102, v120
	v_add_f32_e32 v128, v103, v98
	v_cvt_pk_bf16_f32 v98, v100, v101
	v_cvt_pk_bf16_f32 v99, v102, v103
	s_waitcnt lgkmcnt(6)
	v_mfma_f32_32x32x16_bf16 v[48:63], v[124:127], v[112:115], v[48:63]
	ds_read_b64_tr_b16 v[100:101], v175 offset:24576
	ds_read_b64_tr_b16 v[102:103], v176 offset:24576
	ds_read_b64_tr_b16 v[116:117], v177 offset:24576
	ds_read_b64_tr_b16 v[118:119], v178 offset:24576
	ds_read_b64_tr_b16 v[120:121], v179 offset:24576
	ds_read_b64_tr_b16 v[122:123], v182 offset:24576
	ds_read_b64_tr_b16 v[188:189], v183 offset:24576
	ds_read_b64_tr_b16 v[190:191], v184 offset:24576
	v_exp_f32_e32 v129, v104
	s_nop 0
	v_add_f32_e32 v104, v129, v128
	s_waitcnt lgkmcnt(12)
	v_mfma_f32_32x32x16_bf16 v[32:47], v[208:211], v[112:115], v[32:47]
	v_exp_f32_e32 v128, v105
	s_nop 0
	v_add_f32_e32 v104, v128, v104
	s_waitcnt lgkmcnt(10)
	v_mfma_f32_32x32x16_bf16 v[16:31], v[212:215], v[112:115], v[16:31]
	v_exp_f32_e32 v130, v106
	s_nop 0
	v_add_f32_e32 v104, v130, v104
	s_waitcnt lgkmcnt(8)
	v_mfma_f32_32x32x16_bf16 v[0:15], v[216:219], v[112:115], v[0:15]
	v_exp_f32_e32 v204, v107
	s_nop 0
	v_add_f32_e32 v205, v204, v104
	s_waitcnt lgkmcnt(6)
	v_mfma_f32_32x32x16_bf16 v[48:63], v[100:103], v[96:99], v[48:63]
	ds_read_b64_tr_b16 v[104:105], v175 offset:28672
	ds_read_b64_tr_b16 v[106:107], v176 offset:28672
	ds_read_b64_tr_b16 v[112:113], v177 offset:28672
	ds_read_b64_tr_b16 v[114:115], v178 offset:28672
	ds_read_b64_tr_b16 v[124:125], v179 offset:28672
	ds_read_b64_tr_b16 v[126:127], v182 offset:28672
	ds_read_b64_tr_b16 v[200:201], v183 offset:28672
	ds_read_b64_tr_b16 v[202:203], v184 offset:28672
	v_exp_f32_e32 v108, v108
	s_nop 0
	v_add_f32_e32 v100, v108, v205
	s_waitcnt lgkmcnt(12)
	v_mfma_f32_32x32x16_bf16 v[32:47], v[116:119], v[96:99], v[32:47]
	v_exp_f32_e32 v102, v109
	s_nop 0
	v_add_f32_e32 v100, v102, v100
	s_waitcnt lgkmcnt(10)
	v_mfma_f32_32x32x16_bf16 v[16:31], v[120:123], v[96:99], v[16:31]
	v_exp_f32_e32 v103, v110
	s_nop 0
	v_add_f32_e32 v109, v103, v100
	s_waitcnt lgkmcnt(8)
	v_mfma_f32_32x32x16_bf16 v[0:15], v[188:191], v[96:99], v[0:15]
	v_exp_f32_e32 v110, v111
	v_cvt_pk_bf16_f32 v100, v129, v128
	v_cvt_pk_bf16_f32 v101, v130, v204
	v_cvt_pk_bf16_f32 v102, v108, v102
	v_add_f32_e32 v108, v110, v109
	v_cvt_pk_bf16_f32 v103, v103, v110
	s_waitcnt lgkmcnt(6)
	s_nop 0
	v_mfma_f32_32x32x16_bf16 v[48:63], v[104:107], v[100:103], v[48:63]
	s_waitcnt lgkmcnt(4)
	v_mfma_f32_32x32x16_bf16 v[32:47], v[112:115], v[100:103], v[32:47]
	s_waitcnt lgkmcnt(2)
	v_mfma_f32_32x32x16_bf16 v[16:31], v[124:127], v[100:103], v[16:31]
	s_waitcnt lgkmcnt(0)
	v_mfma_f32_32x32x16_bf16 v[0:15], v[200:203], v[100:103], v[0:15]
	s_waitcnt vmcnt(0) lgkmcnt(0)
	s_barrier
	s_add_i32 s4, s74, 2
	s_add_i32 s5, s74, 1
	v_add_f32_e32 v188, v192, v108
	s_cmp_lt_i32 s5, s20
	s_cbranch_scc0 .LBB0_305
	s_mov_b32 s74, s4
	s_branch .LBB0_301
